# e9 plus differential-attention main loop: each step barrier deferred behind the first two QK MFMAs of the next step (V fragment reads moved after it) so the barrier wait overlaps queued MFMAs
# baseline (speedup 1.0000x reference)
.LBB0_249:
	v_mfma_f32_32x32x16_bf16 v[130:145], v[206:209], v[174:177], 0
	s_mov_b32 s40, s15
	s_mov_b32 s0, s35
	s_mov_b32 s1, s14
	v_lshl_add_u32 v211, s34, 1, v251
	v_add_f32_e32 v67, v98, v99
	v_add_f32_e32 v67, v100, v67
	v_add_f32_e32 v67, v101, v67
	v_add_f32_e32 v67, v102, v67
	v_add_f32_e32 v67, v103, v67
	v_cvt_pk_bf16_f32 v158, v98, v99
	v_cvt_pk_bf16_f32 v159, v100, v101
	v_add_f32_e32 v67, v104, v67
	v_add_f32_e32 v67, v105, v67
	v_add_f32_e32 v67, v106, v67
	v_add_f32_e32 v67, v107, v67
	v_cvt_pk_bf16_f32 v160, v102, v103
	v_cvt_pk_bf16_f32 v161, v104, v105
	v_mfma_f32_32x32x16_bf16 v[114:129], v[198:201], v[174:177], 0
	s_barrier
	ds_read_b64_tr_b16 v[68:69], v211 offset:24576
	ds_read_b64_tr_b16 v[70:71], v211 offset:25088
	ds_read_b64_tr_b16 v[72:73], v211 offset:28672
	ds_read_b64_tr_b16 v[74:75], v211 offset:29184
	ds_read_b64_tr_b16 v[76:77], v211 offset:25600
	ds_read_b64_tr_b16 v[78:79], v211 offset:26112
	v_add_f32_e32 v67, v108, v67
	v_add_f32_e32 v67, v109, v67
	v_add_f32_e32 v67, v110, v67
	v_add_f32_e32 v67, v111, v67
	v_cvt_pk_bf16_f32 v154, v106, v107
	v_cvt_pk_bf16_f32 v155, v108, v109
	s_waitcnt lgkmcnt(11)
	v_mfma_f32_32x32x16_bf16 v[130:145], v[202:205], v[170:173], v[130:145]
	ds_read_b64_tr_b16 v[98:99], v211 offset:29696
	ds_read_b64_tr_b16 v[100:101], v211 offset:30208
	v_add_f32_e32 v67, v112, v67
	v_add_f32_e32 v67, v113, v67
	v_add_f32_e32 v67, v82, v67
	v_add_f32_e32 v67, v83, v67
	v_cvt_pk_bf16_f32 v156, v110, v111
	v_cvt_pk_bf16_f32 v157, v112, v113
	s_waitcnt lgkmcnt(12)
	v_mfma_f32_32x32x16_bf16 v[114:129], v[194:197], v[170:173], v[114:129]
	ds_read_b64_tr_b16 v[102:103], v211 offset:26624
	ds_read_b64_tr_b16 v[104:105], v211 offset:27136
	v_add_f32_e32 v67, v84, v67
	v_add_f32_e32 v67, v85, v67
	v_add_f32_e32 v67, v86, v67
	v_add_f32_e32 v67, v87, v67
	v_cvt_pk_bf16_f32 v150, v82, v83
	v_cvt_pk_bf16_f32 v151, v84, v85
	s_waitcnt lgkmcnt(13)
	v_mfma_f32_32x32x16_bf16 v[130:145], v[190:193], v[166:169], v[130:145]
	ds_read_b64_tr_b16 v[106:107], v211 offset:30720
	ds_read_b64_tr_b16 v[108:109], v211 offset:31232
	v_add_f32_e32 v67, v88, v67
	v_add_f32_e32 v67, v89, v67
	v_add_f32_e32 v67, v90, v67
	v_add_f32_e32 v67, v91, v67
	v_cvt_pk_bf16_f32 v152, v86, v87
	v_cvt_pk_bf16_f32 v153, v88, v89
	s_waitcnt lgkmcnt(14)
	v_mfma_f32_32x32x16_bf16 v[114:129], v[186:189], v[166:169], v[114:129]
	ds_read_b64_tr_b16 v[110:111], v211 offset:27648
	ds_read_b64_tr_b16 v[112:113], v211 offset:28160
	v_add_f32_e32 v67, v92, v67
	v_add_f32_e32 v67, v93, v67
	v_add_f32_e32 v67, v94, v67
	v_add_f32_e32 v67, v95, v67
	v_cvt_pk_bf16_f32 v146, v90, v91
	v_cvt_pk_bf16_f32 v147, v92, v93
	s_waitcnt lgkmcnt(14)
	v_mfma_f32_32x32x16_bf16 v[130:145], v[182:185], v[162:165], v[130:145]
	ds_read_b64_tr_b16 v[88:89], v211 offset:31744
	ds_read_b64_tr_b16 v[90:91], v211 offset:32256
	v_add_f32_e32 v67, v96, v67
	v_add_f32_e32 v67, v97, v67
	v_add_f32_e32 v67, 0, v67
	v_cvt_pk_bf16_f32 v148, v94, v95
	v_cvt_pk_bf16_f32 v149, v96, v97
	v_mfma_f32_32x32x16_bf16 v[114:129], v[178:181], v[162:165], v[114:129]
	v_lshl_add_u64 v[190:191], v[226:227], 0, s[2:3]
	s_add_i32 s14, s14, s18
	v_lshl_add_u64 v[80:81], v[190:191], 0, s[70:71]
	s_mov_b32 s15, m0
	s_mov_b32 m0, s14
	s_nop 0
	global_load_lds_dwordx4 v[80:81], off
	s_mov_b32 m0, s15
	v_lshl_add_u64 v[192:193], v[228:229], 0, s[2:3]
	s_lshl_b32 s14, s40, 1
	v_lshl_add_u64 v[80:81], v[192:193], 0, s[58:59]
	s_add_i32 s14, s14, s19
	s_mov_b32 s15, m0
	s_mov_b32 m0, s14
	s_nop 0
	global_load_lds_dwordx4 v[80:81], off
	s_mov_b32 m0, s15
	v_lshl_add_u64 v[194:195], v[230:231], 0, s[2:3]
	v_lshl_add_u64 v[80:81], v[194:195], 0, s[58:59]
	s_addk_i32 s14, 0x2000
	s_mov_b32 s15, m0
	s_mov_b32 m0, s14
	s_nop 0
	global_load_lds_dwordx4 v[80:81], off
	s_mov_b32 m0, s15
	s_waitcnt lgkmcnt(14)
	v_mfma_f32_32x32x16_bf16 v[34:49], v[158:161], v[68:71], v[34:49]
	v_exp_f32_e32 v130, v130
	v_exp_f32_e32 v131, v131
	ds_read_b64_tr_b16 v[92:93], v211 offset:32768
	ds_read_b64_tr_b16 v[94:95], v211 offset:33280
	s_waitcnt lgkmcnt(14)
	v_mfma_f32_32x32x16_bf16 v[50:65], v[158:161], v[72:75], v[50:65]
	v_exp_f32_e32 v132, v132
	v_exp_f32_e32 v133, v133
	ds_read_b64_tr_b16 v[196:197], v211 offset:36864
	ds_read_b64_tr_b16 v[198:199], v211 offset:37376
	v_add_u32_e32 v68, s40, v249
	ds_read_b128 v[84:87], v68
	ds_read_b128 v[80:83], v68 offset:512
	s_waitcnt lgkmcnt(14)
	v_mfma_f32_32x32x16_bf16 v[34:49], v[154:157], v[76:79], v[34:49]
	v_exp_f32_e32 v134, v134
	v_exp_f32_e32 v135, v135
	ds_read_b64_tr_b16 v[200:201], v211 offset:33792
	ds_read_b64_tr_b16 v[202:203], v211 offset:34304
	ds_read_b128 v[186:189], v68 offset:2048
	ds_read_b128 v[182:185], v68 offset:2560
	v_mfma_f32_32x32x16_bf16 v[50:65], v[154:157], v[98:101], v[50:65]
	v_exp_f32_e32 v136, v136
	v_exp_f32_e32 v137, v137
	ds_read_b64_tr_b16 v[96:97], v211 offset:37888
	ds_read_b64_tr_b16 v[98:99], v211 offset:38400
	ds_read_b128 v[178:181], v68 offset:4096
	ds_read_b128 v[76:79], v68 offset:4608
	s_waitcnt lgkmcnt(14)
	v_mfma_f32_32x32x16_bf16 v[34:49], v[150:153], v[102:105], v[34:49]
	v_exp_f32_e32 v138, v138
	v_exp_f32_e32 v139, v139
	ds_read_b64_tr_b16 v[100:101], v211 offset:34816
	ds_read_b64_tr_b16 v[102:103], v211 offset:35328
	ds_read_b128 v[72:75], v68 offset:6144
	ds_read_b128 v[68:71], v68 offset:6656
	v_mfma_f32_32x32x16_bf16 v[50:65], v[150:153], v[106:109], v[50:65]
	v_exp_f32_e32 v140, v140
	v_exp_f32_e32 v141, v141
	ds_read_b64_tr_b16 v[104:105], v211 offset:38912
	ds_read_b64_tr_b16 v[106:107], v211 offset:39424
	v_mfma_f32_32x32x16_bf16 v[34:49], v[146:149], v[110:113], v[34:49]
	v_exp_f32_e32 v142, v142
	v_exp_f32_e32 v143, v143
	ds_read_b64_tr_b16 v[108:109], v211 offset:35840
	ds_read_b64_tr_b16 v[110:111], v211 offset:36352
	v_mfma_f32_32x32x16_bf16 v[50:65], v[146:149], v[88:91], v[50:65]
	v_exp_f32_e32 v144, v144
	v_exp_f32_e32 v145, v145
	ds_read_b64_tr_b16 v[88:89], v211 offset:39936
	ds_read_b64_tr_b16 v[90:91], v211 offset:40448
	s_waitcnt lgkmcnt(14)
	v_mfma_f32_32x32x16_bf16 v[2:17], v[158:161], v[92:95], v[2:17]
	v_exp_f32_e32 v114, v114
	v_exp_f32_e32 v115, v115
	v_mfma_f32_32x32x16_bf16 v[18:33], v[158:161], v[196:199], v[18:33]
	v_exp_f32_e32 v116, v116
	v_exp_f32_e32 v117, v117
	v_mfma_f32_32x32x16_bf16 v[2:17], v[154:157], v[200:203], v[2:17]
	v_exp_f32_e32 v118, v118
	v_exp_f32_e32 v119, v119
	s_waitcnt lgkmcnt(12)
	v_mfma_f32_32x32x16_bf16 v[18:33], v[154:157], v[96:99], v[18:33]
	v_exp_f32_e32 v120, v120
	v_exp_f32_e32 v121, v121
	s_waitcnt lgkmcnt(8)
	v_mfma_f32_32x32x16_bf16 v[2:17], v[150:153], v[100:103], v[2:17]
	v_exp_f32_e32 v122, v122
	v_exp_f32_e32 v123, v123
	s_waitcnt lgkmcnt(4)
	v_mfma_f32_32x32x16_bf16 v[18:33], v[150:153], v[104:107], v[18:33]
	v_exp_f32_e32 v124, v124
	v_exp_f32_e32 v125, v125
	s_waitcnt lgkmcnt(2)
	v_mfma_f32_32x32x16_bf16 v[2:17], v[146:149], v[108:111], v[2:17]
	v_exp_f32_e32 v126, v126
	v_exp_f32_e32 v127, v127
	v_exp_f32_e32 v128, v128
	v_exp_f32_e32 v129, v129
	s_waitcnt lgkmcnt(0)
	v_mfma_f32_32x32x16_bf16 v[18:33], v[146:149], v[88:91], v[18:33]
	s_waitcnt vmcnt(3) lgkmcnt(0)
	v_mfma_f32_32x32x16_bf16 v[98:113], v[84:87], v[174:177], 0
	s_add_i32 s14, s40, 0x2000
	s_cmpk_lg_i32 s40, 0x4000
	s_cselect_b32 s14, s14, 0
	v_lshl_add_u32 v211, s1, 1, v251
	v_add_f32_e32 v88, v130, v131
	v_add_f32_e32 v88, v132, v88
	v_add_f32_e32 v88, v133, v88
	v_add_f32_e32 v88, v134, v88
	v_add_f32_e32 v88, v135, v88
	v_cvt_pk_bf16_f32 v158, v130, v131
	v_cvt_pk_bf16_f32 v159, v132, v133
	v_add_f32_e32 v84, v136, v88
	v_add_f32_e32 v84, v137, v84
	v_add_f32_e32 v84, v138, v84
	v_add_f32_e32 v146, v139, v84
	v_mfma_f32_32x32x16_bf16 v[82:97], v[80:83], v[174:177], 0
	s_barrier
	ds_read_b64_tr_b16 v[196:197], v211 offset:24576
	ds_read_b64_tr_b16 v[198:199], v211 offset:25088
	ds_read_b64_tr_b16 v[130:131], v211 offset:28672
	ds_read_b64_tr_b16 v[132:133], v211 offset:29184
	v_cvt_pk_bf16_f32 v160, v134, v135
	v_cvt_pk_bf16_f32 v161, v136, v137
	ds_read_b64_tr_b16 v[134:135], v211 offset:25600
	ds_read_b64_tr_b16 v[136:137], v211 offset:26112
	v_mfma_f32_32x32x16_bf16 v[98:113], v[186:189], v[170:173], v[98:113]
	v_add_f32_e32 v80, v140, v146
	v_add_f32_e32 v80, v141, v80
	v_add_f32_e32 v80, v142, v80
	v_add_f32_e32 v80, v143, v80
	v_cvt_pk_bf16_f32 v154, v138, v139
	v_cvt_pk_bf16_f32 v155, v140, v141
	ds_read_b64_tr_b16 v[138:139], v211 offset:29696
	ds_read_b64_tr_b16 v[140:141], v211 offset:30208
	v_mfma_f32_32x32x16_bf16 v[82:97], v[182:185], v[170:173], v[82:97]
	v_add_f32_e32 v80, v144, v80
	v_add_f32_e32 v80, v145, v80
	v_add_f32_e32 v80, v114, v80
	v_add_f32_e32 v80, v115, v80
	v_cvt_pk_bf16_f32 v156, v142, v143
	v_cvt_pk_bf16_f32 v157, v144, v145
	ds_read_b64_tr_b16 v[142:143], v211 offset:26624
	ds_read_b64_tr_b16 v[144:145], v211 offset:27136
	v_mfma_f32_32x32x16_bf16 v[98:113], v[178:181], v[166:169], v[98:113]
	v_add_f32_e32 v80, v116, v80
	v_add_f32_e32 v80, v117, v80
	v_add_f32_e32 v80, v118, v80
	v_add_f32_e32 v80, v119, v80
	v_cvt_pk_bf16_f32 v150, v114, v115
	v_cvt_pk_bf16_f32 v151, v116, v117
	ds_read_b64_tr_b16 v[114:115], v211 offset:30720
	ds_read_b64_tr_b16 v[116:117], v211 offset:31232
	v_mfma_f32_32x32x16_bf16 v[82:97], v[76:79], v[166:169], v[82:97]
	v_add_f32_e32 v76, v120, v80
	v_add_f32_e32 v76, v121, v76
	v_add_f32_e32 v76, v122, v76
	v_add_f32_e32 v80, v123, v76
	v_cvt_pk_bf16_f32 v152, v118, v119
	v_cvt_pk_bf16_f32 v153, v120, v121
	ds_read_b64_tr_b16 v[76:77], v211 offset:27648
	ds_read_b64_tr_b16 v[78:79], v211 offset:28160
	v_mfma_f32_32x32x16_bf16 v[98:113], v[72:75], v[162:165], v[98:113]
	v_add_f32_e32 v72, v124, v80
	v_add_f32_e32 v72, v125, v72
	v_add_f32_e32 v72, v126, v72
	v_add_f32_e32 v80, v127, v72
	v_cvt_pk_bf16_f32 v146, v122, v123
	v_cvt_pk_bf16_f32 v147, v124, v125
	ds_read_b64_tr_b16 v[72:73], v211 offset:31744
	ds_read_b64_tr_b16 v[74:75], v211 offset:32256
	v_mfma_f32_32x32x16_bf16 v[82:97], v[68:71], v[162:165], v[82:97]
	v_add_f32_e32 v68, v128, v80
	v_add_f32_e32 v68, v129, v68
	v_add_f32_e32 v80, 0, v68
	v_cvt_pk_bf16_f32 v148, v126, v127
	v_cvt_pk_bf16_f32 v149, v128, v129
	s_add_i32 s1, s40, s18
	v_lshl_add_u64 v[68:69], v[190:191], 0, s[62:63]
	s_mov_b32 s15, m0
	s_mov_b32 m0, s1
	s_nop 0
	global_load_lds_dwordx4 v[68:69], off
	s_mov_b32 m0, s15
	s_lshl_b32 s1, s14, 1
	v_lshl_add_u64 v[68:69], v[192:193], 0, s[60:61]
	s_add_i32 s1, s1, s19
	s_mov_b32 s15, m0
	s_mov_b32 m0, s1
	s_nop 0
	global_load_lds_dwordx4 v[68:69], off
	s_mov_b32 m0, s15
	v_lshl_add_u64 v[68:69], v[194:195], 0, s[60:61]
	s_addk_i32 s1, 0x2000
	s_mov_b32 s15, m0
	s_mov_b32 m0, s1
	s_nop 0
	global_load_lds_dwordx4 v[68:69], off
	s_mov_b32 m0, s15
	s_waitcnt lgkmcnt(14)
	v_mfma_f32_32x32x16_bf16 v[34:49], v[158:161], v[196:199], v[34:49]
	v_exp_f32_e32 v98, v98
	v_exp_f32_e32 v99, v99
	ds_read_b64_tr_b16 v[68:69], v211 offset:32768
	ds_read_b64_tr_b16 v[70:71], v211 offset:33280
	s_waitcnt lgkmcnt(14)
	v_mfma_f32_32x32x16_bf16 v[50:65], v[158:161], v[130:133], v[50:65]
	v_exp_f32_e32 v100, v100
	v_exp_f32_e32 v101, v101
	ds_read_b64_tr_b16 v[118:119], v211 offset:36864
	ds_read_b64_tr_b16 v[120:121], v211 offset:37376
	v_add_u32_e32 v81, s14, v249
	ds_read_b128 v[206:209], v81
	ds_read_b128 v[198:201], v81 offset:512
	s_waitcnt lgkmcnt(14)
	v_mfma_f32_32x32x16_bf16 v[34:49], v[154:157], v[134:137], v[34:49]
	v_exp_f32_e32 v102, v102
	v_exp_f32_e32 v103, v103
	ds_read_b64_tr_b16 v[122:123], v211 offset:33792
	ds_read_b64_tr_b16 v[124:125], v211 offset:34304
	ds_read_b128 v[202:205], v81 offset:2048
	ds_read_b128 v[194:197], v81 offset:2560
	v_mfma_f32_32x32x16_bf16 v[50:65], v[154:157], v[138:141], v[50:65]
	v_exp_f32_e32 v104, v104
	v_exp_f32_e32 v105, v105
	ds_read_b64_tr_b16 v[126:127], v211 offset:37888
	ds_read_b64_tr_b16 v[128:129], v211 offset:38400
	ds_read_b128 v[190:193], v81 offset:4096
	ds_read_b128 v[186:189], v81 offset:4608
	s_waitcnt lgkmcnt(14)
	v_mfma_f32_32x32x16_bf16 v[34:49], v[150:153], v[142:145], v[34:49]
	v_exp_f32_e32 v106, v106
	v_exp_f32_e32 v107, v107
	ds_read_b64_tr_b16 v[130:131], v211 offset:34816
	ds_read_b64_tr_b16 v[132:133], v211 offset:35328
	ds_read_b128 v[182:185], v81 offset:6144
	ds_read_b128 v[178:181], v81 offset:6656
	v_mfma_f32_32x32x16_bf16 v[50:65], v[150:153], v[114:117], v[50:65]
	v_exp_f32_e32 v108, v108
	v_exp_f32_e32 v109, v109
	ds_read_b64_tr_b16 v[114:115], v211 offset:38912
	ds_read_b64_tr_b16 v[116:117], v211 offset:39424
	v_mfma_f32_32x32x16_bf16 v[34:49], v[146:149], v[76:79], v[34:49]
	v_exp_f32_e32 v110, v110
	v_exp_f32_e32 v111, v111
	ds_read_b64_tr_b16 v[76:77], v211 offset:35840
	ds_read_b64_tr_b16 v[78:79], v211 offset:36352
	v_mfma_f32_32x32x16_bf16 v[50:65], v[146:149], v[72:75], v[50:65]
	v_exp_f32_e32 v112, v112
	v_exp_f32_e32 v113, v113
	ds_read_b64_tr_b16 v[72:73], v211 offset:39936
	ds_read_b64_tr_b16 v[74:75], v211 offset:40448
	s_waitcnt lgkmcnt(14)
	v_mfma_f32_32x32x16_bf16 v[2:17], v[158:161], v[68:71], v[2:17]
	v_exp_f32_e32 v82, v82
	v_exp_f32_e32 v83, v83
	v_mfma_f32_32x32x16_bf16 v[18:33], v[158:161], v[118:121], v[18:33]
	v_exp_f32_e32 v84, v84
	v_exp_f32_e32 v85, v85
	v_mfma_f32_32x32x16_bf16 v[2:17], v[154:157], v[122:125], v[2:17]
	v_exp_f32_e32 v86, v86
	v_exp_f32_e32 v87, v87
	s_waitcnt lgkmcnt(12)
	v_mfma_f32_32x32x16_bf16 v[18:33], v[154:157], v[126:129], v[18:33]
	v_exp_f32_e32 v88, v88
	v_exp_f32_e32 v89, v89
	s_waitcnt lgkmcnt(8)
	v_mfma_f32_32x32x16_bf16 v[2:17], v[150:153], v[130:133], v[2:17]
	v_exp_f32_e32 v90, v90
	v_exp_f32_e32 v91, v91
	s_waitcnt lgkmcnt(4)
	v_mfma_f32_32x32x16_bf16 v[18:33], v[150:153], v[114:117], v[18:33]
	v_exp_f32_e32 v92, v92
	v_exp_f32_e32 v93, v93
	s_waitcnt lgkmcnt(2)
	v_mfma_f32_32x32x16_bf16 v[2:17], v[146:149], v[76:79], v[2:17]
	v_exp_f32_e32 v94, v94
	v_exp_f32_e32 v95, v95
	v_exp_f32_e32 v96, v96
	v_exp_f32_e32 v97, v97
	s_add_i32 s1, s14, 0x2000
	s_cmpk_lg_i32 s14, 0x4000
	s_cselect_b32 s15, s1, 0
	s_add_i32 s35, s35, 2
	s_add_u32 s2, s2, 0x40000
	v_add_f32_e32 v66, v66, v67
	s_addc_u32 s3, s3, 0
	s_mov_b32 s34, s40
	v_add_f32_e32 v66, v66, v80
	s_cmp_ge_u32 s35, s29
	s_waitcnt lgkmcnt(0)
	v_mfma_f32_32x32x16_bf16 v[18:33], v[146:149], v[72:75], v[18:33]
	s_waitcnt vmcnt(3) lgkmcnt(0)
	s_cbranch_scc0 .LBB0_249
	s_barrier
	s_add_i32 s50, s0, -5
	s_lshl_b64 s[86:87], s[4:5], 10
	s_add_i32 s0, s50, 1
	s_cmp_lt_u32 s0, s29
	s_cbranch_scc0 .LBB0_254
